# P3 late-weight f32->bf16 transposes rewritten by hand: 8 row loads in flight per item (was 8 serialized load-wait round trips)
# baseline (speedup 1.0000x reference)
.LBB0_436:
	v_mbcnt_lo_u32_b32 v0, -1, 0
	v_mbcnt_hi_u32_b32 v0, -1, v0
	v_lshrrev_b32_e32 v1, 3, v0
	v_and_b32_e32 v2, 7, v0
	v_readlane_b32 s0, v235, 17
	s_lshl_b32 s1, s0, 14
	v_mul_u32_u24_e32 v3, 33, v1
	v_lshl_add_u32 v3, v2, 2, v3
	v_lshl_add_u32 v192, v3, 2, s1
	v_add_u32_e32 v193, 0x420, v192
	v_add_u32_e32 v194, 0x840, v192
	v_add_u32_e32 v195, 0xc60, v192
	v_add_u32_e32 v196, 0x1080, v192
	v_add_u32_e32 v197, 0x14a0, v192
	v_add_u32_e32 v198, 0x18c0, v192
	v_add_u32_e32 v199, 0x1ce0, v192
	v_mul_u32_u24_e32 v3, 0x108, v2
	v_add_u32_e32 v3, v3, v1
	v_lshl_add_u32 v200, v3, 2, s1
	v_lshlrev_b32_e32 v4, 4, v2
	v_lshl_add_u32 v201, v1, 13, v4
	v_mul_u32_u24_e32 v5, 0xb000, v1
	v_add_u32_e32 v202, v5, v4
	v_lshl_add_u32 v203, v1, 11, v4
	v_lshl_add_u32 v204, v1, 12, v4
	v_mul_u32_u24_e32 v5, 0x2c00, v1
	v_add_u32_e32 v205, v5, v4
	s_lshl_b32 s8, s96, 3
	s_add_i32 s8, s8, s0
	s_add_i32 s8, s8, 0xffffff00
	v_readlane_b32 s36, v235, 7
	v_readlane_b32 s37, v235, 8
	v_readlane_b32 s38, v235, 9
	v_readlane_b32 s39, v235, 10
	v_readlane_b32 s40, v235, 11
	v_readlane_b32 s41, v235, 12
	v_readlane_b32 s42, v235, 15
	v_readlane_b32 s43, v235, 16
	v_readlane_b32 s44, v235, 50
	v_readlane_b32 s45, v235, 51
	v_readlane_b32 s46, v235, 52
	v_readlane_b32 s47, v235, 53
	v_readlane_b32 s48, v235, 54
	v_readlane_b32 s49, v235, 55
	v_readlane_b32 s50, v235, 56
	v_readlane_b32 s51, v235, 57
	v_readlane_b32 s18, v235, 58
	v_readlane_b32 s19, v235, 59
.Llw_loop:
	s_cmpk_gt_i32 s8, 0x51ff
	s_cbranch_scc1 .Llw_done
	s_mov_b32 s9, s8
	s_cmpk_lt_i32 s9, 0x400
	s_cbranch_scc0 .Llw_c1
	s_mov_b64 s[26:27], s[36:37]
	s_mov_b64 s[28:29], s[44:45]
	s_movk_i32 s20, 0x800
	s_movk_i32 s21, 0x400
	s_and_b32 s22, s9, 0xffffffc0
	s_and_b32 s23, s9, 63
	s_lshl_b32 s23, s23, 5
	s_mov_b32 s24, s23
	v_mov_b32_e32 v206, v201
	v_mov_b32_e32 v207, v203
	s_branch .Llw_go
.Llw_c1:
	s_addk_i32 s9, 0xfc00
	s_cmpk_lt_i32 s9, 0x400
	s_cbranch_scc0 .Llw_c2
	s_mov_b64 s[26:27], s[38:39]
	s_mov_b64 s[28:29], s[46:47]
	s_movk_i32 s20, 0x800
	s_movk_i32 s21, 0x400
	s_and_b32 s22, s9, 0xffffffc0
	s_and_b32 s23, s9, 63
	s_lshl_b32 s23, s23, 5
	s_mov_b32 s24, s23
	v_mov_b32_e32 v206, v201
	v_mov_b32_e32 v207, v203
	s_branch .Llw_go
.Llw_c2:
	s_addk_i32 s9, 0xfc00
	s_cmpk_lt_i32 s9, 0x800
	s_cbranch_scc0 .Llw_c3
	s_mov_b64 s[26:27], s[40:41]
	s_mov_b64 s[28:29], s[48:49]
	s_movk_i32 s20, 0x800
	s_movk_i32 s21, 0x800
	s_and_b32 s22, s9, 0xffffffc0
	s_and_b32 s23, s9, 63
	s_lshl_b32 s23, s23, 5
	s_mov_b32 s24, s23
	v_mov_b32_e32 v206, v201
	v_mov_b32_e32 v207, v204
	s_branch .Llw_go
.Llw_c3:
	s_addk_i32 s9, 0xf800
	s_cmpk_lt_i32 s9, 0x2c00
	s_cbranch_scc0 .Llw_c4
	s_mov_b64 s[26:27], s[42:43]
	s_mov_b64 s[28:29], s[50:51]
	s_movk_i32 s20, 0x2c00
	s_movk_i32 s21, 0x800
	s_lshr_b32 s2, s9, 5
	s_mulk_i32 s2, 0x1746
	s_lshr_b32 s2, s2, 16
	s_mul_i32 s3, s2, 0x160
	s_sub_i32 s3, s9, s3
	s_lshl_b32 s22, s2, 6
	s_lshl_b32 s23, s3, 5
	s_lshr_b32 s24, s23, 8
	s_lshl_b32 s24, s24, 7
	s_and_b32 s2, s23, 127
	s_add_i32 s24, s24, s2
	s_bitcmp1_b32 s23, 7
	s_cselect_b32 s2, 0x1600, 0
	s_add_i32 s24, s24, s2
	v_mov_b32_e32 v206, v202
	v_mov_b32_e32 v207, v204
	s_branch .Llw_go
.Llw_c4:
	s_addk_i32 s9, 0xd400
	s_mov_b64 s[26:27], s[84:85]
	s_mov_b64 s[28:29], s[18:19]
	s_movk_i32 s20, 0x800
	s_movk_i32 s21, 0x1600
	s_and_b32 s22, s9, 0xffffffc0
	s_and_b32 s23, s9, 63
	s_lshl_b32 s23, s23, 5
	s_mov_b32 s24, s23
	v_mov_b32_e32 v206, v201
	v_mov_b32_e32 v207, v205
.Llw_go:
	s_mul_i32 s2, s22, s20
	s_add_i32 s2, s2, s24
	s_lshl_b32 s2, s2, 2
	s_add_u32 s26, s26, s2
	s_addc_u32 s27, s27, 0
	s_lshl_b32 s30, s20, 5
	global_load_dwordx4 v[96:99], v206, s[26:27]
	s_add_u32 s26, s26, s30
	s_addc_u32 s27, s27, 0
	global_load_dwordx4 v[100:103], v206, s[26:27]
	s_add_u32 s26, s26, s30
	s_addc_u32 s27, s27, 0
	global_load_dwordx4 v[104:107], v206, s[26:27]
	s_add_u32 s26, s26, s30
	s_addc_u32 s27, s27, 0
	global_load_dwordx4 v[108:111], v206, s[26:27]
	s_add_u32 s26, s26, s30
	s_addc_u32 s27, s27, 0
	global_load_dwordx4 v[112:115], v206, s[26:27]
	s_add_u32 s26, s26, s30
	s_addc_u32 s27, s27, 0
	global_load_dwordx4 v[116:119], v206, s[26:27]
	s_add_u32 s26, s26, s30
	s_addc_u32 s27, s27, 0
	global_load_dwordx4 v[120:123], v206, s[26:27]
	s_add_u32 s26, s26, s30
	s_addc_u32 s27, s27, 0
	global_load_dwordx4 v[124:127], v206, s[26:27]
	s_mul_i32 s3, s23, s21
	s_add_i32 s3, s3, s22
	s_lshl_b32 s3, s3, 1
	s_add_u32 s28, s28, s3
	s_addc_u32 s29, s29, 0
	s_lshl_b32 s31, s21, 4
	s_waitcnt vmcnt(7)
	ds_write2_b32 v192, v96, v97 offset1:1
	ds_write2_b32 v192, v98, v99 offset0:2 offset1:3
	s_waitcnt vmcnt(6)
	ds_write2_b32 v193, v100, v101 offset1:1
	ds_write2_b32 v193, v102, v103 offset0:2 offset1:3
	s_waitcnt vmcnt(5)
	ds_write2_b32 v194, v104, v105 offset1:1
	ds_write2_b32 v194, v106, v107 offset0:2 offset1:3
	s_waitcnt vmcnt(4)
	ds_write2_b32 v195, v108, v109 offset1:1
	ds_write2_b32 v195, v110, v111 offset0:2 offset1:3
	s_waitcnt vmcnt(3)
	ds_write2_b32 v196, v112, v113 offset1:1
	ds_write2_b32 v196, v114, v115 offset0:2 offset1:3
	s_waitcnt vmcnt(2)
	ds_write2_b32 v197, v116, v117 offset1:1
	ds_write2_b32 v197, v118, v119 offset0:2 offset1:3
	s_waitcnt vmcnt(1)
	ds_write2_b32 v198, v120, v121 offset1:1
	ds_write2_b32 v198, v122, v123 offset0:2 offset1:3
	s_waitcnt vmcnt(0)
	ds_write2_b32 v199, v124, v125 offset1:1
	ds_write2_b32 v199, v126, v127 offset0:2 offset1:3
	s_waitcnt lgkmcnt(0)
	ds_read2_b32 v[0:1], v200 offset0:0 offset1:8
	ds_read2_b32 v[2:3], v200 offset0:33 offset1:41
	ds_read2_b32 v[4:5], v200 offset0:66 offset1:74
	ds_read2_b32 v[6:7], v200 offset0:99 offset1:107
	ds_read2_b32 v[8:9], v200 offset0:132 offset1:140
	ds_read2_b32 v[10:11], v200 offset0:165 offset1:173
	ds_read2_b32 v[12:13], v200 offset0:198 offset1:206
	ds_read2_b32 v[14:15], v200 offset0:231 offset1:239
	s_waitcnt lgkmcnt(0)
	v_cvt_pk_bf16_f32 v16, v0, v2
	v_cvt_pk_bf16_f32 v17, v4, v6
	v_cvt_pk_bf16_f32 v18, v8, v10
	v_cvt_pk_bf16_f32 v19, v12, v14
	v_cvt_pk_bf16_f32 v20, v1, v3
	v_cvt_pk_bf16_f32 v21, v5, v7
	v_cvt_pk_bf16_f32 v22, v9, v11
	v_cvt_pk_bf16_f32 v23, v13, v15
	global_store_dwordx4 v207, v[16:19], s[28:29]
	s_add_u32 s28, s28, s31
	s_addc_u32 s29, s29, 0
	global_store_dwordx4 v207, v[20:23], s[28:29]
	s_add_u32 s28, s28, s31
	s_addc_u32 s29, s29, 0
	ds_read2_b32 v[0:1], v200 offset0:16 offset1:24
	ds_read2_b32 v[2:3], v200 offset0:49 offset1:57
	ds_read2_b32 v[4:5], v200 offset0:82 offset1:90
	ds_read2_b32 v[6:7], v200 offset0:115 offset1:123
	ds_read2_b32 v[8:9], v200 offset0:148 offset1:156
	ds_read2_b32 v[10:11], v200 offset0:181 offset1:189
	ds_read2_b32 v[12:13], v200 offset0:214 offset1:222
	ds_read2_b32 v[14:15], v200 offset0:247 offset1:255
	s_waitcnt lgkmcnt(0)
	v_cvt_pk_bf16_f32 v16, v0, v2
	v_cvt_pk_bf16_f32 v17, v4, v6
	v_cvt_pk_bf16_f32 v18, v8, v10
	v_cvt_pk_bf16_f32 v19, v12, v14
	v_cvt_pk_bf16_f32 v20, v1, v3
	v_cvt_pk_bf16_f32 v21, v5, v7
	v_cvt_pk_bf16_f32 v22, v9, v11
	v_cvt_pk_bf16_f32 v23, v13, v15
	global_store_dwordx4 v207, v[16:19], s[28:29]
	s_add_u32 s28, s28, s31
	s_addc_u32 s29, s29, 0
	global_store_dwordx4 v207, v[20:23], s[28:29]
	s_add_u32 s28, s28, s31
	s_addc_u32 s29, s29, 0
	s_addk_i32 s8, 0x700
	s_branch .Llw_loop
.Llw_done:
	s_branch .LBB0_568
	s_lshl_b32 s0, s96, 3
	v_readlane_b32 s1, v235, 17
	s_add_i32 s0, s0, s1
	s_add_i32 s8, s0, 0xffffff00
	s_cmpk_gt_i32 s8, 0x51ff
	v_mbcnt_lo_u32_b32 v0, -1, 0
	v_mbcnt_hi_u32_b32 v0, -1, v0
	s_cbranch_scc1 .LBB0_568
	v_readlane_b32 s0, v235, 17
	s_lshl_b32 s0, s0, 14
	v_and_b32_e32 v1, 7, v0
	v_ashrrev_i32_e32 v210, 3, v0
	s_add_i32 s0, s0, 0
	v_lshlrev_b32_e32 v209, 2, v1
	v_lshlrev_b32_e32 v192, 4, v1
	s_movk_i32 s1, 0x84
	v_mul_u32_u24_e32 v0, 0x420, v1
	v_lshlrev_b32_e32 v1, 2, v210
	v_add_u32_e32 v211, s0, v192
	v_mul_lo_u32 v212, v210, s1
	v_add3_u32 v216, s0, v0, v1
	v_readlane_b32 s0, v235, 56
	v_mov_b32_e32 v193, 0
	v_readlane_b32 s1, v235, 57
	v_readlane_b32 s2, v235, 58
	s_add_i32 s9, s88, 0xffffff00
	v_lshl_add_u64 v[196:197], s[0:1], 0, v[192:193]
	v_readlane_b32 s0, v235, 54
	v_readlane_b32 s1, v235, 55
	v_readlane_b32 s3, v235, 59
	s_mov_b32 s7, 0
	v_lshl_add_u64 v[198:199], s[0:1], 0, v[192:193]
	v_readlane_b32 s0, v235, 52
	v_readlane_b32 s1, v235, 53
	v_add_u32_e32 v213, 8, v210
	v_add_u32_e32 v214, 16, v210
	v_lshl_add_u64 v[200:201], s[0:1], 0, v[192:193]
	v_readlane_b32 s0, v235, 50
	v_readlane_b32 s1, v235, 51
	v_add_u32_e32 v215, 24, v210
	v_lshl_add_u64 v[194:195], s[2:3], 0, v[192:193]
	v_lshl_add_u64 v[202:203], s[0:1], 0, v[192:193]
	s_lshl_b32 s10, s8, 5
	s_lshl_b32 s11, s9, 5
	s_movk_i32 s18, 0x7e0
	s_movk_i32 s19, 0x2c00
	s_movk_i32 s20, 0x800
	s_mov_b32 s21, 0xb000
	s_movk_i32 s22, 0x7f8
	s_movk_i32 s23, 0x7f0
	s_movk_i32 s24, 0x7e8
	s_movk_i32 s25, 0x7d8
	s_movk_i32 s26, 0x7d0
	s_movk_i32 s27, 0x7c8
	s_movk_i32 s28, 0x400
	s_movk_i32 s29, 0x3e0
	s_movk_i32 s30, 0x3d8
	s_movk_i32 s31, 0x3d0
	s_movk_i32 s33, 0x3c8
	s_branch .LBB0_441
